# asm guide 7.5: v_pk_add_f32 beside MFMAs in the MLA/NSA attention tile loops split into scalar v_add_f32 pairs
# speedup vs baseline: 1.0059x; 1.0021x over previous
; DEVI float fexp2(float x) { return __builtin_amdgcn_exp2f(x); }
; template <int M> DEVI float shx(float v) { return __int_as_float(__builtin_amdgcn_ds_swizzle(__float_as_int(v), (M << 10) | 0x1f)); }
; DEVI float shx32(float v, int lane) { return __int_as_float(__builtin_amdgcn_ds_bpermute((lane ^ 32) << 2, __float_as_int(v))); }
; DEVI bf16x8 pack_p(const f32x4& a, const f32x4& b) { return as_bf8((u32x4){pk2(a[0], a[1]), pk2(a[2], a[3]), pk2(b[0], b[1]), pk2(b[2], b[3])}); }
; template <int NC, int KS, class MaskF>
; DEVI void attn_tile(const unsigned char* Kl, int krow, const unsigned char* Vl, const bf16x8 (&q)[NC][KS], f32x4 (&o)[NC][4],
;                     float (&mr)[NC], float (&lr)[NC], int idx, int quad, int mask_mode, bool lane_ok, const MaskF& mf) {
;     ...
;       float ps = 0.f;
;       f32x4 p0, p1;
; #pragma unroll
;       for (int j = 0; j < 4; ++j) { p0[j] = fexp2(s[c][0][j] - mr[c]); p1[j] = fexp2(s[c][1][j] - mr[c]); ps += p0[j] + p1[j]; }
;       if (__builtin_amdgcn_ballot_w64(!(ps <= 2048.f)) != 0ull) {
;         float mx = fmaxf(fmaxf(fmaxf(s[c][0][0], s[c][0][1]), fmaxf(s[c][0][2], s[c][0][3])), fmaxf(fmaxf(s[c][1][0], s[c][1][1]), fmaxf(s[c][1][2], s[c][1][3])));
;         mx = fmaxf(mx, shx<16>(mx)); mx = fmaxf(mx, shx32(mx, quad * 16 + idx));
;         const float mnew = fmaxf(mr[c], mx);
;         const float alpha = fexp2(mr[c] - mnew);
;         lr[c] *= alpha; mr[c] = mnew;
; #pragma unroll
;         for (int dvt = 0; dvt < 4; ++dvt) o[c][dvt] *= alpha;
;         ps = 0.f;
; #pragma unroll
;         for (int j = 0; j < 4; ++j) { p0[j] = fexp2(s[c][0][j] - mnew); p1[j] = fexp2(s[c][1][j] - mnew); ps += p0[j] + p1[j]; }
;       }
;       lr[c] += ps;
;       s[c][0] = p0; s[c][1] = p1;
;       pb[c] = pack_p(s[c][0], s[c][1]);
.LBB0_1371:
	s_or_b64 exec, exec, s[12:13]
	v_sub_f32_e32 v32, v78, v100
	v_exp_f32_e32 v127, v32
	s_nop 1
	v_sub_f32_e32 v32, v82, v100
	v_exp_f32_e32 v128, v32
	v_sub_f32_e32 v32, v79, v100
	v_sub_f32_e32 v102, v83, v100
	v_exp_f32_e32 v32, v32
	v_exp_f32_e32 v102, v102
	v_add_f32_e32 v103, v128, v127
	v_add_f32_e32 v104, v102, v32
	v_add_f32_e32 v105, v103, v33
	v_sub_f32_e32 v103, v80, v100
	v_exp_f32_e32 v129, v103
	v_sub_f32_e32 v103, v84, v100
	v_add_f32_e32 v105, v104, v105
	v_add_f32_e32 v104, v104, v104
	v_exp_f32_e32 v131, v103
	v_sub_f32_e32 v103, v81, v100
	v_exp_f32_e32 v104, v103
	v_sub_f32_e32 v103, v85, v100
	v_exp_f32_e32 v106, v103
	v_add_f32_e32 v107, v131, v129
	v_add_f32_e32 v132, v106, v104
	v_add_f32_e32 v133, v107, v105
	s_nop 0
	v_add_f32_e32 v103, v132, v133
	v_cmp_nge_f32_e32 vcc, s94, v103
	s_cbranch_vccz .LBB0_1373
	v_max_f32_e32 v32, v79, v79
	v_max_f32_e32 v102, v78, v78
	v_max_f32_e32 v32, v102, v32
	v_max_f32_e32 v102, v81, v81
	v_max_f32_e32 v103, v80, v80
	v_max_f32_e32 v102, v103, v102
	v_max_f32_e32 v103, v85, v85
	v_max_f32_e32 v104, v84, v84
	v_max_f32_e32 v103, v104, v103
	v_max3_f32 v103, v82, v83, v103
	v_max3_f32 v32, v32, v102, v103
	ds_swizzle_b32 v102, v32 offset:swizzle(SWAP,16)
	v_mov_b32_e32 v103, v33
	v_mov_b32_e32 v133, v101
	s_waitcnt lgkmcnt(0)
	v_max_f32_e32 v102, v102, v102
	v_max_f32_e32 v32, v32, v102
	ds_bpermute_b32 v102, v110, v32
	s_waitcnt lgkmcnt(0)
	v_max3_f32 v132, v100, v32, v102
	v_sub_f32_e32 v32, v100, v132
	v_exp_f32_e32 v32, v32
	v_mov_b64_e32 v[100:101], v[132:133]
	v_mul_f32_e32 v92, v92, v32
	v_pk_mul_f32 v[68:69], v[68:69], v[32:33] op_sel_hi:[1,0]
	v_pk_mul_f32 v[66:67], v[66:67], v[32:33] op_sel_hi:[1,0]
	v_pk_mul_f32 v[64:65], v[64:65], v[32:33] op_sel_hi:[1,0]
	v_pk_mul_f32 v[62:63], v[62:63], v[32:33] op_sel_hi:[1,0]
	v_pk_mul_f32 v[60:61], v[60:61], v[32:33] op_sel_hi:[1,0]
	v_pk_mul_f32 v[58:59], v[58:59], v[32:33] op_sel_hi:[1,0]
	v_pk_mul_f32 v[56:57], v[56:57], v[32:33] op_sel_hi:[1,0]
	v_pk_mul_f32 v[54:55], v[54:55], v[32:33] op_sel_hi:[1,0]
	v_sub_f32_e32 v32, v78, v132
	v_exp_f32_e32 v127, v32
	v_sub_f32_e32 v32, v82, v132
	v_exp_f32_e32 v128, v32
	v_sub_f32_e32 v32, v79, v132
	v_exp_f32_e32 v134, v32
	v_sub_f32_e32 v32, v83, v132
	v_exp_f32_e32 v102, v32
	v_sub_f32_e32 v32, v80, v132
	v_add_f32_e32 v135, v127, v128
	v_exp_f32_e32 v129, v32
	v_sub_f32_e32 v32, v84, v132
	v_add_f32_e32 v78, v134, v102
	v_add_f32_e32 v79, v135, v103
	v_exp_f32_e32 v131, v32
	v_sub_f32_e32 v32, v81, v132
	v_add_f32_e32 v106, v78, v78
	v_add_f32_e32 v107, v78, v79
	v_exp_f32_e32 v104, v32
	v_sub_f32_e32 v32, v85, v132
	v_exp_f32_e32 v106, v32
	v_add_f32_e32 v105, v129, v131
	v_mov_b32_e32 v32, v134
	v_add_f32_e32 v78, v104, v106
	v_add_f32_e32 v79, v105, v107
	s_nop 0
	v_add_f32_e32 v103, v78, v79

; DEVI float fexp2(float x) { return __builtin_amdgcn_exp2f(x); }
; template <int M> DEVI float shx(float v) { return __int_as_float(__builtin_amdgcn_ds_swizzle(__float_as_int(v), (M << 10) | 0x1f)); }
; DEVI float shx32(float v, int lane) { return __int_as_float(__builtin_amdgcn_ds_bpermute((lane ^ 32) << 2, __float_as_int(v))); }
; DEVI bf16x8 pack_p(const f32x4& a, const f32x4& b) { return as_bf8((u32x4){pk2(a[0], a[1]), pk2(a[2], a[3]), pk2(b[0], b[1]), pk2(b[2], b[3])}); }
; template <int NC, int KS, class MaskF>
; DEVI void attn_tile(const unsigned char* Kl, int krow, const unsigned char* Vl, const bf16x8 (&q)[NC][KS], f32x4 (&o)[NC][4],
;                     float (&mr)[NC], float (&lr)[NC], int idx, int quad, int mask_mode, bool lane_ok, const MaskF& mf) {
;     ...
;       float ps = 0.f;
;       f32x4 p0, p1;
; #pragma unroll
;       for (int j = 0; j < 4; ++j) { p0[j] = fexp2(s[c][0][j] - mr[c]); p1[j] = fexp2(s[c][1][j] - mr[c]); ps += p0[j] + p1[j]; }
;       if (__builtin_amdgcn_ballot_w64(!(ps <= 2048.f)) != 0ull) {
;         float mx = fmaxf(fmaxf(fmaxf(s[c][0][0], s[c][0][1]), fmaxf(s[c][0][2], s[c][0][3])), fmaxf(fmaxf(s[c][1][0], s[c][1][1]), fmaxf(s[c][1][2], s[c][1][3])));
;         mx = fmaxf(mx, shx<16>(mx)); mx = fmaxf(mx, shx32(mx, quad * 16 + idx));
;         const float mnew = fmaxf(mr[c], mx);
;         const float alpha = fexp2(mr[c] - mnew);
;         lr[c] *= alpha; mr[c] = mnew;
; #pragma unroll
;         for (int dvt = 0; dvt < 4; ++dvt) o[c][dvt] *= alpha;
;         ps = 0.f;
; #pragma unroll
;         for (int j = 0; j < 4; ++j) { p0[j] = fexp2(s[c][0][j] - mnew); p1[j] = fexp2(s[c][1][j] - mnew); ps += p0[j] + p1[j]; }
;       }
;       lr[c] += ps;
;       s[c][0] = p0; s[c][1] = p1;
;       pb[c] = pack_p(s[c][0], s[c][1]);
.LBB0_1375:
	s_or_b64 exec, exec, s[12:13]
	v_sub_f32_e32 v32, v70, v101
	v_exp_f32_e32 v104, v32
	v_sub_f32_e32 v32, v74, v101
	v_exp_f32_e32 v105, v32
	v_sub_f32_e32 v32, v71, v101
	v_sub_f32_e32 v82, v75, v101
	v_exp_f32_e32 v32, v32
	v_exp_f32_e32 v82, v82
	v_add_f32_e32 v83, v105, v104
	v_sub_f32_e32 v102, v77, v101
	v_exp_f32_e32 v102, v102
	v_add_f32_e32 v84, v82, v32
	v_add_f32_e32 v85, v83, v33
	v_sub_f32_e32 v83, v72, v101
	v_add_f32_e32 v85, v84, v85
	v_add_f32_e32 v84, v84, v84
	v_sub_f32_e32 v84, v76, v101
	v_exp_f32_e32 v83, v83
	v_exp_f32_e32 v106, v84
	v_sub_f32_e32 v84, v73, v101
	v_exp_f32_e32 v84, v84
	v_add_f32_e32 v92, v103, v92
	v_add_f32_e32 v103, v106, v83
	v_add_f32_e32 v126, v102, v84
	v_add_f32_e32 v127, v103, v85
	s_nop 0
	v_add_f32_e32 v107, v126, v127
	v_cmp_nge_f32_e32 vcc, s94, v107
	s_cbranch_vccz .LBB0_1377
	v_max_f32_e32 v32, v71, v71
	v_max_f32_e32 v82, v70, v70
	v_max_f32_e32 v32, v82, v32
	v_max_f32_e32 v82, v73, v73
	v_max_f32_e32 v83, v72, v72
	v_max_f32_e32 v82, v83, v82
	v_max_f32_e32 v83, v77, v77
	v_max_f32_e32 v84, v76, v76
	v_max_f32_e32 v83, v84, v83
	v_max3_f32 v83, v74, v75, v83
	v_max3_f32 v32, v32, v82, v83
	ds_swizzle_b32 v82, v32 offset:swizzle(SWAP,16)
	v_mov_b32_e32 v83, v33
	s_waitcnt lgkmcnt(0)
	v_max_f32_e32 v82, v82, v82
	v_max_f32_e32 v32, v32, v82
	ds_bpermute_b32 v82, v110, v32
	s_waitcnt lgkmcnt(0)
	v_max3_f32 v107, v101, v32, v82
	v_sub_f32_e32 v32, v101, v107
	v_exp_f32_e32 v32, v32
	v_mov_b32_e32 v101, v107
	v_mul_f32_e32 v93, v93, v32
	v_pk_mul_f32 v[52:53], v[52:53], v[32:33] op_sel_hi:[1,0]
	v_pk_mul_f32 v[50:51], v[50:51], v[32:33] op_sel_hi:[1,0]
	v_pk_mul_f32 v[48:49], v[48:49], v[32:33] op_sel_hi:[1,0]
	v_pk_mul_f32 v[46:47], v[46:47], v[32:33] op_sel_hi:[1,0]
	v_pk_mul_f32 v[44:45], v[44:45], v[32:33] op_sel_hi:[1,0]
	v_pk_mul_f32 v[42:43], v[42:43], v[32:33] op_sel_hi:[1,0]
	v_pk_mul_f32 v[40:41], v[40:41], v[32:33] op_sel_hi:[1,0]
	v_pk_mul_f32 v[38:39], v[38:39], v[32:33] op_sel_hi:[1,0]
	v_sub_f32_e32 v32, v70, v107
	v_exp_f32_e32 v104, v32
	v_sub_f32_e32 v32, v74, v107
	v_exp_f32_e32 v105, v32
	v_sub_f32_e32 v32, v71, v107
	v_exp_f32_e32 v126, v32
	v_sub_f32_e32 v32, v75, v107
	v_exp_f32_e32 v82, v32
	v_add_f32_e32 v127, v104, v105
	v_sub_f32_e32 v32, v72, v107
	v_add_f32_e32 v70, v126, v82
	v_add_f32_e32 v71, v127, v83
	v_exp_f32_e32 v83, v32
	v_sub_f32_e32 v32, v76, v107
	v_exp_f32_e32 v106, v32
	v_sub_f32_e32 v32, v73, v107
	v_add_f32_e32 v102, v70, v70
	v_add_f32_e32 v103, v70, v71
	v_exp_f32_e32 v84, v32
	v_sub_f32_e32 v32, v77, v107
	v_exp_f32_e32 v102, v32
	v_add_f32_e32 v85, v83, v106
	v_mov_b32_e32 v32, v126
	v_add_f32_e32 v70, v84, v102
	v_add_f32_e32 v71, v85, v103
	s_nop 0
	v_add_f32_e32 v107, v70, v71

; DEVI float fexp2(float x) { return __builtin_amdgcn_exp2f(x); }
; template <int M> DEVI float shx(float v) { return __int_as_float(__builtin_amdgcn_ds_swizzle(__float_as_int(v), (M << 10) | 0x1f)); }
; DEVI float shx32(float v, int lane) { return __int_as_float(__builtin_amdgcn_ds_bpermute((lane ^ 32) << 2, __float_as_int(v))); }
; DEVI bf16x8 pack_p(const f32x4& a, const f32x4& b) { return as_bf8((u32x4){pk2(a[0], a[1]), pk2(a[2], a[3]), pk2(b[0], b[1]), pk2(b[2], b[3])}); }
; template <int NC, int KS, class MaskF>
; DEVI void attn_tile(const unsigned char* Kl, int krow, const unsigned char* Vl, const bf16x8 (&q)[NC][KS], f32x4 (&o)[NC][4],
;                     float (&mr)[NC], float (&lr)[NC], int idx, int quad, int mask_mode, bool lane_ok, const MaskF& mf) {
;     ...
;       float ps = 0.f;
;       f32x4 p0, p1;
; #pragma unroll
;       for (int j = 0; j < 4; ++j) { p0[j] = fexp2(s[c][0][j] - mr[c]); p1[j] = fexp2(s[c][1][j] - mr[c]); ps += p0[j] + p1[j]; }
;       if (__builtin_amdgcn_ballot_w64(!(ps <= 2048.f)) != 0ull) {
;         float mx = fmaxf(fmaxf(fmaxf(s[c][0][0], s[c][0][1]), fmaxf(s[c][0][2], s[c][0][3])), fmaxf(fmaxf(s[c][1][0], s[c][1][1]), fmaxf(s[c][1][2], s[c][1][3])));
;         mx = fmaxf(mx, shx<16>(mx)); mx = fmaxf(mx, shx32(mx, quad * 16 + idx));
;         const float mnew = fmaxf(mr[c], mx);
;         const float alpha = fexp2(mr[c] - mnew);
;         lr[c] *= alpha; mr[c] = mnew;
; #pragma unroll
;         for (int dvt = 0; dvt < 4; ++dvt) o[c][dvt] *= alpha;
;         ps = 0.f;
; #pragma unroll
;         for (int j = 0; j < 4; ++j) { p0[j] = fexp2(s[c][0][j] - mnew); p1[j] = fexp2(s[c][1][j] - mnew); ps += p0[j] + p1[j]; }
;       }
;       lr[c] += ps;
;       s[c][0] = p0; s[c][1] = p1;
;       pb[c] = pack_p(s[c][0], s[c][1]);
.LBB0_1379:
	s_or_b64 exec, exec, s[12:13]
	v_sub_f32_e32 v32, v78, v100
	v_exp_f32_e32 v124, v32
	s_nop 1
	v_sub_f32_e32 v32, v82, v100
	v_exp_f32_e32 v136, v32
	v_sub_f32_e32 v32, v79, v100
	v_sub_f32_e32 v102, v83, v100
	v_exp_f32_e32 v32, v32
	v_exp_f32_e32 v102, v102
	v_add_f32_e32 v103, v136, v124
	v_add_f32_e32 v93, v107, v93
	v_add_f32_e32 v104, v102, v32
	v_add_f32_e32 v105, v103, v33
	v_sub_f32_e32 v103, v80, v100
	v_exp_f32_e32 v137, v103
	v_sub_f32_e32 v103, v84, v100
	v_add_f32_e32 v105, v104, v105
	v_add_f32_e32 v104, v104, v104
	v_exp_f32_e32 v138, v103
	v_sub_f32_e32 v103, v81, v100
	v_exp_f32_e32 v104, v103
	v_sub_f32_e32 v103, v85, v100
	v_exp_f32_e32 v106, v103
	v_add_f32_e32 v107, v138, v137
	v_add_f32_e32 v132, v106, v104
	v_add_f32_e32 v133, v107, v105
	s_nop 0
	v_add_f32_e32 v103, v132, v133
	v_cmp_nge_f32_e32 vcc, s94, v103
	s_cbranch_vccz .LBB0_1381
	v_max_f32_e32 v32, v79, v79
	v_max_f32_e32 v102, v78, v78
	v_max_f32_e32 v32, v102, v32
	v_max_f32_e32 v102, v81, v81
	v_max_f32_e32 v103, v80, v80
	v_max_f32_e32 v102, v103, v102
	v_max_f32_e32 v103, v85, v85
	v_max_f32_e32 v104, v84, v84
	v_max_f32_e32 v103, v104, v103
	v_max3_f32 v103, v82, v83, v103
	v_max3_f32 v32, v32, v102, v103
	ds_swizzle_b32 v102, v32 offset:swizzle(SWAP,16)
	v_mov_b32_e32 v103, v33
	v_mov_b32_e32 v133, v101
	s_waitcnt lgkmcnt(0)
	v_max_f32_e32 v102, v102, v102
	v_max_f32_e32 v32, v32, v102
	ds_bpermute_b32 v102, v110, v32
	s_waitcnt lgkmcnt(0)
	v_max3_f32 v132, v100, v32, v102
	v_sub_f32_e32 v32, v100, v132
	v_exp_f32_e32 v32, v32
	v_mov_b64_e32 v[100:101], v[132:133]
	v_mul_f32_e32 v92, v92, v32
	v_pk_mul_f32 v[68:69], v[68:69], v[32:33] op_sel_hi:[1,0]
	v_pk_mul_f32 v[66:67], v[66:67], v[32:33] op_sel_hi:[1,0]
	v_pk_mul_f32 v[64:65], v[64:65], v[32:33] op_sel_hi:[1,0]
	v_pk_mul_f32 v[62:63], v[62:63], v[32:33] op_sel_hi:[1,0]
	v_pk_mul_f32 v[60:61], v[60:61], v[32:33] op_sel_hi:[1,0]
	v_pk_mul_f32 v[58:59], v[58:59], v[32:33] op_sel_hi:[1,0]
	v_pk_mul_f32 v[56:57], v[56:57], v[32:33] op_sel_hi:[1,0]
	v_pk_mul_f32 v[54:55], v[54:55], v[32:33] op_sel_hi:[1,0]
	v_sub_f32_e32 v32, v78, v132
	v_exp_f32_e32 v124, v32
	v_sub_f32_e32 v32, v82, v132
	v_exp_f32_e32 v136, v32
	v_sub_f32_e32 v32, v79, v132
	v_exp_f32_e32 v134, v32
	v_sub_f32_e32 v32, v83, v132
	v_exp_f32_e32 v102, v32
	v_sub_f32_e32 v32, v80, v132
	v_add_f32_e32 v135, v124, v136
	v_exp_f32_e32 v137, v32
	v_sub_f32_e32 v32, v84, v132
	v_add_f32_e32 v78, v134, v102
	v_add_f32_e32 v79, v135, v103
	v_exp_f32_e32 v138, v32
	v_sub_f32_e32 v32, v81, v132
	v_add_f32_e32 v106, v78, v78
	v_add_f32_e32 v107, v78, v79
	v_exp_f32_e32 v104, v32
	v_sub_f32_e32 v32, v85, v132
	v_exp_f32_e32 v106, v32
	v_add_f32_e32 v105, v137, v138
	v_mov_b32_e32 v32, v134
	v_add_f32_e32 v78, v104, v106
	v_add_f32_e32 v79, v105, v107
	s_nop 0
	v_add_f32_e32 v103, v78, v79

; DEVI float fexp2(float x) { return __builtin_amdgcn_exp2f(x); }
; template <int M> DEVI float shx(float v) { return __int_as_float(__builtin_amdgcn_ds_swizzle(__float_as_int(v), (M << 10) | 0x1f)); }
; DEVI float shx32(float v, int lane) { return __int_as_float(__builtin_amdgcn_ds_bpermute((lane ^ 32) << 2, __float_as_int(v))); }
; DEVI bf16x8 pack_p(const f32x4& a, const f32x4& b) { return as_bf8((u32x4){pk2(a[0], a[1]), pk2(a[2], a[3]), pk2(b[0], b[1]), pk2(b[2], b[3])}); }
; template <int NC, int KS, class MaskF>
; DEVI void attn_tile(const unsigned char* Kl, int krow, const unsigned char* Vl, const bf16x8 (&q)[NC][KS], f32x4 (&o)[NC][4],
;                     float (&mr)[NC], float (&lr)[NC], int idx, int quad, int mask_mode, bool lane_ok, const MaskF& mf) {
;     ...
;       float ps = 0.f;
;       f32x4 p0, p1;
; #pragma unroll
;       for (int j = 0; j < 4; ++j) { p0[j] = fexp2(s[c][0][j] - mr[c]); p1[j] = fexp2(s[c][1][j] - mr[c]); ps += p0[j] + p1[j]; }
;       if (__builtin_amdgcn_ballot_w64(!(ps <= 2048.f)) != 0ull) {
;         float mx = fmaxf(fmaxf(fmaxf(s[c][0][0], s[c][0][1]), fmaxf(s[c][0][2], s[c][0][3])), fmaxf(fmaxf(s[c][1][0], s[c][1][1]), fmaxf(s[c][1][2], s[c][1][3])));
;         mx = fmaxf(mx, shx<16>(mx)); mx = fmaxf(mx, shx32(mx, quad * 16 + idx));
;         const float mnew = fmaxf(mr[c], mx);
;         const float alpha = fexp2(mr[c] - mnew);
;         lr[c] *= alpha; mr[c] = mnew;
; #pragma unroll
;         for (int dvt = 0; dvt < 4; ++dvt) o[c][dvt] *= alpha;
;         ps = 0.f;
; #pragma unroll
;         for (int j = 0; j < 4; ++j) { p0[j] = fexp2(s[c][0][j] - mnew); p1[j] = fexp2(s[c][1][j] - mnew); ps += p0[j] + p1[j]; }
;       }
;       lr[c] += ps;
;       s[c][0] = p0; s[c][1] = p1;
;       pb[c] = pack_p(s[c][0], s[c][1]);
.LBB0_1383:
	s_or_b64 exec, exec, s[12:13]
	v_sub_f32_e32 v32, v70, v101
	v_exp_f32_e32 v104, v32
	v_sub_f32_e32 v32, v74, v101
	v_exp_f32_e32 v105, v32
	v_sub_f32_e32 v32, v71, v101
	v_sub_f32_e32 v82, v75, v101
	v_exp_f32_e32 v32, v32
	v_exp_f32_e32 v82, v82
	v_add_f32_e32 v83, v105, v104
	v_sub_f32_e32 v102, v77, v101
	v_exp_f32_e32 v102, v102
	v_add_f32_e32 v84, v82, v32
	v_add_f32_e32 v85, v83, v33
	v_sub_f32_e32 v83, v72, v101
	v_add_f32_e32 v85, v84, v85
	v_add_f32_e32 v84, v84, v84
	v_sub_f32_e32 v84, v76, v101
	v_exp_f32_e32 v83, v83
	v_exp_f32_e32 v106, v84
	v_sub_f32_e32 v84, v73, v101
	v_exp_f32_e32 v84, v84
	v_add_f32_e32 v92, v103, v92
	v_add_f32_e32 v103, v106, v83
	v_add_f32_e32 v132, v102, v84
	v_add_f32_e32 v133, v103, v85
	s_nop 0
	v_add_f32_e32 v85, v132, v133
	v_cmp_nge_f32_e32 vcc, s94, v85
	s_cbranch_vccz .LBB0_1385
	v_max_f32_e32 v32, v71, v71
	v_max_f32_e32 v82, v70, v70
	v_max_f32_e32 v32, v82, v32
	v_max_f32_e32 v82, v73, v73
	v_max_f32_e32 v83, v72, v72
	v_max_f32_e32 v82, v83, v82
	v_max_f32_e32 v83, v77, v77
	v_max_f32_e32 v84, v76, v76
	v_max_f32_e32 v83, v84, v83
	v_max3_f32 v83, v74, v75, v83
	v_max3_f32 v32, v32, v82, v83
	ds_swizzle_b32 v82, v32 offset:swizzle(SWAP,16)
	v_mov_b32_e32 v83, v33
	s_waitcnt lgkmcnt(0)
	v_max_f32_e32 v82, v82, v82
	v_max_f32_e32 v32, v32, v82
	ds_bpermute_b32 v82, v110, v32
	s_waitcnt lgkmcnt(0)
	v_max3_f32 v107, v101, v32, v82
	v_sub_f32_e32 v32, v101, v107
	v_exp_f32_e32 v32, v32
	v_mov_b32_e32 v101, v107
	v_mul_f32_e32 v93, v93, v32
	v_pk_mul_f32 v[52:53], v[52:53], v[32:33] op_sel_hi:[1,0]
	v_pk_mul_f32 v[50:51], v[50:51], v[32:33] op_sel_hi:[1,0]
	v_pk_mul_f32 v[48:49], v[48:49], v[32:33] op_sel_hi:[1,0]
	v_pk_mul_f32 v[46:47], v[46:47], v[32:33] op_sel_hi:[1,0]
	v_pk_mul_f32 v[44:45], v[44:45], v[32:33] op_sel_hi:[1,0]
	v_pk_mul_f32 v[42:43], v[42:43], v[32:33] op_sel_hi:[1,0]
	v_pk_mul_f32 v[40:41], v[40:41], v[32:33] op_sel_hi:[1,0]
	v_pk_mul_f32 v[38:39], v[38:39], v[32:33] op_sel_hi:[1,0]
	v_sub_f32_e32 v32, v70, v107
	v_exp_f32_e32 v104, v32
	v_sub_f32_e32 v32, v74, v107
	v_exp_f32_e32 v105, v32
	v_sub_f32_e32 v32, v71, v107
	v_exp_f32_e32 v132, v32
	v_sub_f32_e32 v32, v75, v107
	v_exp_f32_e32 v82, v32
	v_add_f32_e32 v133, v104, v105
	v_sub_f32_e32 v32, v72, v107
	v_add_f32_e32 v70, v132, v82
	v_add_f32_e32 v71, v133, v83
	v_exp_f32_e32 v83, v32
	v_sub_f32_e32 v32, v76, v107
	v_exp_f32_e32 v106, v32
	v_sub_f32_e32 v32, v73, v107
	v_add_f32_e32 v102, v70, v70
	v_add_f32_e32 v103, v70, v71
	v_exp_f32_e32 v84, v32
	v_sub_f32_e32 v32, v77, v107
	v_exp_f32_e32 v102, v32
	v_add_f32_e32 v85, v83, v106
	v_mov_b32_e32 v32, v132
	v_add_f32_e32 v70, v84, v102
	v_add_f32_e32 v71, v85, v103
	s_nop 0
	v_add_f32_e32 v85, v70, v71

; DEVI float bf2f(bf16_t b) { return __uint_as_float(((unsigned)b) << 16); }
; DEVI float sigmoidf(float x) { return 1.f / (1.f + __expf(-x)); }
; template <int M> DEVI float shx(float v) { return __int_as_float(__builtin_amdgcn_ds_swizzle(__float_as_int(v), (M << 10) | 0x1f)); }
; DEVI float shx32(float v, int lane) { return __int_as_float(__builtin_amdgcn_ds_bpermute((lane ^ 32) << 2, __float_as_int(v))); }
; DEVI void nsa_item(const Ctx& cx, const unsigned* cflag, int b, int g, int qt, unsigned char* lds, int wv) {
;     ...
;     if (is_win && !in_win) {
;       in_win = true;
;       const bf16_t* gp = proj + (size_t)(tokrow * (unsigned)PS + (unsigned)(C_GATE + g * 9));
; #pragma unroll
;       for (int c = 0; c < 3; ++c) {
;         float lt = lrn[c]; lt += shx<16>(lt); lt += shx32(lt, quad * 16 + idx);
;         const float gt = sigmoidf(bf2f(gp[c * 3 + 1])) * (lt > 0.f ? 1.f / lt : 0.f);
; #pragma unroll
;         for (int d = 0; d < 4; ++d) { scr[c * 4 + d] += o[c][d] * gt; o[c][d] = (f32x4){0.f, 0.f, 0.f, 0.f}; }
;         mr[c] = -1e29f; lrn[c] = 0.f;
;       }
;     }
.LBB0_1424:
	s_ff1_i32_b64 s3, s[0:1]
	s_cmp_lt_u32 s3, 32
	s_cselect_b64 s[20:21], -1, 0
	s_cmp_gt_u32 s3, 31
	s_cselect_b64 s[4:5], -1, 0
	s_or_b64 s[0:1], s[20:21], s[14:15]
	s_and_b64 vcc, exec, s[0:1]
	s_cbranch_vccnz .LBB0_1426
	ds_swizzle_b32 v32, v148 offset:swizzle(SWAP,16)
	v_mov_b32_e32 v145, 0xefa18f08
	v_mov_b32_e32 v146, 0xefa18f08
	v_mov_b32_e32 v147, 0xefa18f08
	s_waitcnt lgkmcnt(0)
	v_add_f32_e32 v32, v148, v32
	ds_bpermute_b32 v34, v122, v32
	v_mov_b32_e32 v148, 0
	s_waitcnt lgkmcnt(0)
	v_add_f32_e32 v32, v32, v34
	global_load_ushort v34, v[110:111], off offset:2
	s_waitcnt vmcnt(0)
	v_lshlrev_b32_e32 v34, 16, v34
	v_mul_f32_e32 v34, 0xbfb8aa3b, v34
	v_exp_f32_e32 v34, v34
	s_nop 0
	v_add_f32_e32 v34, 1.0, v34
	v_div_scale_f32 v35, s[0:1], v34, v34, 1.0
	v_rcp_f32_e32 v84, v35
	v_cmp_lt_f32_e64 s[0:1], 0, v32
	v_fma_f32 v85, -v35, v84, 1.0
	v_fmac_f32_e32 v84, v85, v84
	v_div_scale_f32 v85, vcc, 1.0, v34, 1.0
	v_mul_f32_e32 v86, v85, v84
	v_fma_f32 v87, -v35, v86, v85
	v_fmac_f32_e32 v86, v87, v84
	v_fma_f32 v35, -v35, v86, v85
	v_div_fmas_f32 v35, v35, v84, v86
	v_div_fixup_f32 v34, v35, v34, 1.0
	v_div_scale_f32 v35, s[14:15], v32, v32, 1.0
	v_rcp_f32_e32 v84, v35
	s_nop 0
	v_fma_f32 v85, -v35, v84, 1.0
	v_fmac_f32_e32 v84, v85, v84
	v_div_scale_f32 v85, vcc, 1.0, v32, 1.0
	v_mul_f32_e32 v86, v85, v84
	v_fma_f32 v87, -v35, v86, v85
	v_fmac_f32_e32 v86, v87, v84
	v_fma_f32 v35, -v35, v86, v85
	v_div_fmas_f32 v35, v35, v84, v86
	global_load_dwordx4 v[84:87], v[108:109], off offset:48
	global_load_dwordx4 v[88:91], v[108:109], off offset:32
	global_load_dwordx4 v[92:95], v[108:109], off offset:16
	global_load_dwordx4 v[96:99], v[108:109], off
	v_div_fixup_f32 v32, v35, v32, 1.0
	v_cndmask_b32_e64 v32, 0, v32, s[0:1]
	v_mul_f32_e32 v32, v32, v34
	ds_swizzle_b32 v35, v117 offset:swizzle(SWAP,16)
	s_waitcnt vmcnt(3)
	v_pk_fma_f32 v[70:71], v[70:71], v[32:33], v[86:87] op_sel_hi:[1,0,1]
	s_waitcnt vmcnt(2)
	v_pk_fma_f32 v[74:75], v[74:75], v[32:33], v[90:91] op_sel_hi:[1,0,1]
	s_waitcnt vmcnt(1)
	v_pk_fma_f32 v[78:79], v[78:79], v[32:33], v[94:95] op_sel_hi:[1,0,1]
	s_waitcnt vmcnt(0)
	v_pk_fma_f32 v[82:83], v[82:83], v[32:33], v[98:99] op_sel_hi:[1,0,1]
	v_pk_fma_f32 v[80:81], v[80:81], v[32:33], v[96:97] op_sel_hi:[1,0,1]
	v_pk_fma_f32 v[76:77], v[76:77], v[32:33], v[92:93] op_sel_hi:[1,0,1]
	v_pk_fma_f32 v[72:73], v[72:73], v[32:33], v[88:89] op_sel_hi:[1,0,1]
	v_pk_fma_f32 v[68:69], v[68:69], v[32:33], v[84:85] op_sel_hi:[1,0,1]
	global_store_dwordx4 v[108:109], v[80:83], off
	global_store_dwordx4 v[108:109], v[76:79], off offset:16
	global_store_dwordx4 v[108:109], v[72:75], off offset:32
	global_store_dwordx4 v[108:109], v[68:71], off offset:48
	global_load_ushort v32, v[110:111], off offset:8
	s_waitcnt vmcnt(0)
	v_lshlrev_b32_e32 v32, 16, v32
	v_mul_f32_e32 v32, 0xbfb8aa3b, v32
	v_exp_f32_e32 v32, v32
	s_nop 0
	v_add_f32_e32 v32, 1.0, v32
	v_div_scale_f32 v34, s[0:1], v32, v32, 1.0
	v_rcp_f32_e32 v68, v34
	s_nop 0
	v_fma_f32 v69, -v34, v68, 1.0
	v_fmac_f32_e32 v68, v69, v68
	v_div_scale_f32 v69, vcc, 1.0, v32, 1.0
	v_mul_f32_e32 v70, v69, v68
	v_fma_f32 v71, -v34, v70, v69
	v_fmac_f32_e32 v70, v71, v68
	v_fma_f32 v34, -v34, v70, v69
	v_div_fmas_f32 v34, v34, v68, v70
	global_load_dwordx4 v[68:71], v[108:109], off offset:112
	global_load_dwordx4 v[72:75], v[108:109], off offset:96
	global_load_dwordx4 v[76:79], v[108:109], off offset:80
	global_load_dwordx4 v[80:83], v[108:109], off offset:64
	v_div_fixup_f32 v32, v34, v32, 1.0
	ds_swizzle_b32 v34, v116 offset:swizzle(SWAP,16)
	s_waitcnt lgkmcnt(0)
	v_add_f32_e32 v34, v116, v34
	v_add_f32_e32 v35, v117, v35
	ds_bpermute_b32 v85, v122, v35
	ds_bpermute_b32 v84, v122, v34
	v_mov_b32_e32 v116, 0
	v_mov_b32_e32 v117, v148
	s_waitcnt lgkmcnt(0)
	v_add_f32_e32 v34, v34, v84
	v_add_f32_e32 v35, v35, v85
	s_nop 0
	v_div_scale_f32 v84, s[0:1], v35, v35, 1.0
	v_rcp_f32_e32 v85, v84
	v_cmp_lt_f32_e64 s[0:1], 0, v34
	v_fma_f32 v86, -v84, v85, 1.0
	v_fmac_f32_e32 v85, v86, v85
	v_div_scale_f32 v86, vcc, 1.0, v35, 1.0
	v_mul_f32_e32 v87, v86, v85
	v_fma_f32 v88, -v84, v87, v86
	v_fmac_f32_e32 v87, v88, v85
	v_fma_f32 v84, -v84, v87, v86
	v_div_fmas_f32 v84, v84, v85, v87
	v_div_fixup_f32 v84, v84, v35, 1.0
	v_cmp_lt_f32_e32 vcc, 0, v35
	s_nop 1
	v_cndmask_b32_e32 v35, 0, v84, vcc
	v_mul_f32_e32 v32, v35, v32
	s_waitcnt vmcnt(3)
; DEVI float bf2f(bf16_t b) { return __uint_as_float(((unsigned)b) << 16); }
; DEVI float sigmoidf(float x) { return 1.f / (1.f + __expf(-x)); }
; template <int M> DEVI float shx(float v) { return __int_as_float(__builtin_amdgcn_ds_swizzle(__float_as_int(v), (M << 10) | 0x1f)); }
; DEVI float shx32(float v, int lane) { return __int_as_float(__builtin_amdgcn_ds_bpermute((lane ^ 32) << 2, __float_as_int(v))); }
; DEVI void nsa_item(const Ctx& cx, const unsigned* cflag, int b, int g, int qt, unsigned char* lds, int wv) {
;     ...
; #pragma unroll
;       for (int c = 0; c < 3; ++c) {
;         float lt = lrn[c]; lt += shx<16>(lt); lt += shx32(lt, quad * 16 + idx);
;         const float gt = sigmoidf(bf2f(gp[c * 3 + 1])) * (lt > 0.f ? 1.f / lt : 0.f);
; #pragma unroll
;         for (int d = 0; d < 4; ++d) { scr[c * 4 + d] += o[c][d] * gt; o[c][d] = (f32x4){0.f, 0.f, 0.f, 0.f}; }
;         mr[c] = -1e29f; lrn[c] = 0.f;
;       }
	v_pk_fma_f32 v[54:55], v[54:55], v[32:33], v[70:71] op_sel_hi:[1,0,1]
	s_waitcnt vmcnt(2)
	v_pk_fma_f32 v[58:59], v[58:59], v[32:33], v[74:75] op_sel_hi:[1,0,1]
	s_waitcnt vmcnt(1)
	v_pk_fma_f32 v[62:63], v[62:63], v[32:33], v[78:79] op_sel_hi:[1,0,1]
	s_waitcnt vmcnt(0)
	v_pk_fma_f32 v[66:67], v[66:67], v[32:33], v[82:83] op_sel_hi:[1,0,1]
	v_pk_fma_f32 v[64:65], v[64:65], v[32:33], v[80:81] op_sel_hi:[1,0,1]
	v_pk_fma_f32 v[60:61], v[60:61], v[32:33], v[76:77] op_sel_hi:[1,0,1]
	v_pk_fma_f32 v[56:57], v[56:57], v[32:33], v[72:73] op_sel_hi:[1,0,1]
	v_pk_fma_f32 v[52:53], v[52:53], v[32:33], v[68:69] op_sel_hi:[1,0,1]
	global_store_dwordx4 v[108:109], v[64:67], off offset:64
	global_store_dwordx4 v[108:109], v[60:63], off offset:80
	global_store_dwordx4 v[108:109], v[56:59], off offset:96
	global_store_dwordx4 v[108:109], v[52:55], off offset:112
	global_load_ushort v32, v[110:111], off offset:14
	s_waitcnt vmcnt(0)
	v_lshlrev_b32_e32 v32, 16, v32
	v_mul_f32_e32 v32, 0xbfb8aa3b, v32
	v_exp_f32_e32 v32, v32
	s_nop 0
	v_add_f32_e32 v32, 1.0, v32
	v_div_scale_f32 v35, s[14:15], v32, v32, 1.0
	v_rcp_f32_e32 v52, v35
	s_nop 0
	v_fma_f32 v53, -v35, v52, 1.0
	v_fmac_f32_e32 v52, v53, v52
	v_div_scale_f32 v53, vcc, 1.0, v32, 1.0
	v_mul_f32_e32 v54, v53, v52
	v_fma_f32 v55, -v35, v54, v53
	v_fmac_f32_e32 v54, v55, v52
	v_fma_f32 v35, -v35, v54, v53
	v_div_fmas_f32 v35, v35, v52, v54
	v_div_fixup_f32 v32, v35, v32, 1.0
	v_div_scale_f32 v35, s[14:15], v34, v34, 1.0
	v_rcp_f32_e32 v52, v35
	s_mov_b64 s[14:15], -1
	v_fma_f32 v53, -v35, v52, 1.0
	v_fmac_f32_e32 v52, v53, v52
	v_div_scale_f32 v53, vcc, 1.0, v34, 1.0
	v_mul_f32_e32 v54, v53, v52
	v_fma_f32 v55, -v35, v54, v53
	v_fmac_f32_e32 v54, v55, v52
	v_fma_f32 v35, -v35, v54, v53
	v_div_fmas_f32 v35, v35, v52, v54
	global_load_dwordx4 v[52:55], v[108:109], off offset:176
	global_load_dwordx4 v[56:59], v[108:109], off offset:160
	global_load_dwordx4 v[60:63], v[108:109], off offset:144
	global_load_dwordx4 v[64:67], v[108:109], off offset:128
	v_div_fixup_f32 v34, v35, v34, 1.0
	v_cndmask_b32_e64 v34, 0, v34, s[0:1]
	v_mul_f32_e32 v32, v34, v32
	v_mov_b32_e32 v34, v33
	v_mov_b32_e32 v35, v33
	s_waitcnt vmcnt(3)
	v_pk_fma_f32 v[38:39], v[38:39], v[32:33], v[54:55] op_sel_hi:[1,0,1]
	s_waitcnt vmcnt(2)
	v_pk_fma_f32 v[42:43], v[42:43], v[32:33], v[58:59] op_sel_hi:[1,0,1]
	s_waitcnt vmcnt(1)
	v_pk_fma_f32 v[46:47], v[46:47], v[32:33], v[62:63] op_sel_hi:[1,0,1]
	s_waitcnt vmcnt(0)
	v_pk_fma_f32 v[50:51], v[50:51], v[32:33], v[66:67] op_sel_hi:[1,0,1]
	v_pk_fma_f32 v[48:49], v[48:49], v[32:33], v[64:65] op_sel_hi:[1,0,1]
	v_pk_fma_f32 v[44:45], v[44:45], v[32:33], v[60:61] op_sel_hi:[1,0,1]
	v_pk_fma_f32 v[40:41], v[40:41], v[32:33], v[56:57] op_sel_hi:[1,0,1]
	v_pk_fma_f32 v[36:37], v[36:37], v[32:33], v[52:53] op_sel_hi:[1,0,1]
	global_store_dwordx4 v[108:109], v[48:51], off offset:128
	global_store_dwordx4 v[108:109], v[44:47], off offset:144
	global_store_dwordx4 v[108:109], v[40:43], off offset:160
	global_store_dwordx4 v[108:109], v[36:39], off offset:176
	v_mov_b32_e32 v32, v33
	v_mov_b64_e32 v[82:83], v[34:35]
	v_mov_b64_e32 v[78:79], v[34:35]
	v_mov_b64_e32 v[74:75], v[34:35]
	v_mov_b64_e32 v[70:71], v[34:35]
	v_mov_b64_e32 v[66:67], v[34:35]
	v_mov_b64_e32 v[62:63], v[34:35]
	v_mov_b64_e32 v[58:59], v[34:35]
	v_mov_b64_e32 v[54:55], v[34:35]
	v_mov_b64_e32 v[50:51], v[34:35]
	v_mov_b64_e32 v[46:47], v[34:35]
	v_mov_b64_e32 v[42:43], v[34:35]
	v_mov_b64_e32 v[38:39], v[34:35]
	v_mov_b64_e32 v[80:81], v[32:33]
	v_mov_b64_e32 v[76:77], v[32:33]
	v_mov_b64_e32 v[72:73], v[32:33]
	v_mov_b64_e32 v[68:69], v[32:33]
	v_mov_b64_e32 v[64:65], v[32:33]
	v_mov_b64_e32 v[60:61], v[32:33]
	v_mov_b64_e32 v[56:57], v[32:33]
	v_mov_b64_e32 v[52:53], v[32:33]
	v_mov_b64_e32 v[48:49], v[32:33]
	v_mov_b64_e32 v[44:45], v[32:33]
	v_mov_b64_e32 v[40:41], v[32:33]
	v_mov_b64_e32 v[36:37], v[32:33]

; DEVI float fexp2(float x) { return __builtin_amdgcn_exp2f(x); }
; template <int M> DEVI float shx(float v) { return __int_as_float(__builtin_amdgcn_ds_swizzle(__float_as_int(v), (M << 10) | 0x1f)); }
; DEVI float shx32(float v, int lane) { return __int_as_float(__builtin_amdgcn_ds_bpermute((lane ^ 32) << 2, __float_as_int(v))); }
; DEVI bf16x8 pack_p(const f32x4& a, const f32x4& b) { return as_bf8((u32x4){pk2(a[0], a[1]), pk2(a[2], a[3]), pk2(b[0], b[1]), pk2(b[2], b[3])}); }
; template <int NC, int KS, class MaskF>
; DEVI void attn_tile(const unsigned char* Kl, int krow, const unsigned char* Vl, const bf16x8 (&q)[NC][KS], f32x4 (&o)[NC][4],
;                     float (&mr)[NC], float (&lr)[NC], int idx, int quad, int mask_mode, bool lane_ok, const MaskF& mf) {
;     ...
;       float ps = 0.f;
;       f32x4 p0, p1;
; #pragma unroll
;       for (int j = 0; j < 4; ++j) { p0[j] = fexp2(s[c][0][j] - mr[c]); p1[j] = fexp2(s[c][1][j] - mr[c]); ps += p0[j] + p1[j]; }
;       if (__builtin_amdgcn_ballot_w64(!(ps <= 2048.f)) != 0ull) {
;         float mx = fmaxf(fmaxf(fmaxf(s[c][0][0], s[c][0][1]), fmaxf(s[c][0][2], s[c][0][3])), fmaxf(fmaxf(s[c][1][0], s[c][1][1]), fmaxf(s[c][1][2], s[c][1][3])));
;         mx = fmaxf(mx, shx<16>(mx)); mx = fmaxf(mx, shx32(mx, quad * 16 + idx));
;         const float mnew = fmaxf(mr[c], mx);
;         const float alpha = fexp2(mr[c] - mnew);
;         lr[c] *= alpha; mr[c] = mnew;
; #pragma unroll
;         for (int dvt = 0; dvt < 4; ++dvt) o[c][dvt] *= alpha;
;         ps = 0.f;
; #pragma unroll
;         for (int j = 0; j < 4; ++j) { p0[j] = fexp2(s[c][0][j] - mnew); p1[j] = fexp2(s[c][1][j] - mnew); ps += p0[j] + p1[j]; }
;       }
;       lr[c] += ps;
;       s[c][0] = p0; s[c][1] = p1;
;       pb[c] = pack_p(s[c][0], s[c][1]);
.LBB0_1444:
	s_or_b64 exec, exec, s[4:5]
	v_sub_f32_e32 v32, v92, v145
	v_exp_f32_e32 v159, v32
	v_sub_f32_e32 v32, v104, v145
	v_exp_f32_e32 v156, v32
	v_sub_f32_e32 v32, v93, v145
	v_sub_f32_e32 v34, v105, v145
	v_exp_f32_e32 v32, v32
	v_exp_f32_e32 v34, v34
	v_add_f32_e32 v35, v156, v159
	v_add_f32_e32 v118, v34, v32
	v_add_f32_e32 v119, v35, v33
	v_sub_f32_e32 v35, v94, v145
	v_add_f32_e32 v120, v118, v118
	v_add_f32_e32 v121, v118, v119
	v_exp_f32_e32 v160, v35
	v_sub_f32_e32 v35, v106, v145
	v_sub_f32_e32 v118, v95, v145
	v_exp_f32_e32 v35, v35
	v_exp_f32_e32 v120, v118
	v_sub_f32_e32 v118, v107, v145
	v_exp_f32_e32 v118, v118
	v_add_f32_e32 v119, v35, v160
	v_add_f32_e32 v132, v118, v120
	v_add_f32_e32 v133, v119, v121
	s_nop 0
	v_add_f32_e32 v119, v132, v133
	v_cmp_nge_f32_e32 vcc, s94, v119
	s_cbranch_vccz .LBB0_1446
	v_max_f32_e32 v32, v93, v93
	v_max_f32_e32 v34, v92, v92
	v_max_f32_e32 v32, v34, v32
	v_max_f32_e32 v34, v95, v95
	v_max_f32_e32 v35, v94, v94
	v_max_f32_e32 v34, v35, v34
	v_max_f32_e32 v35, v107, v107
	v_max_f32_e32 v118, v106, v106
	v_max_f32_e32 v35, v118, v35
	v_max3_f32 v35, v104, v105, v35
	v_max3_f32 v32, v32, v34, v35
	ds_swizzle_b32 v34, v32 offset:swizzle(SWAP,16)
	v_mov_b32_e32 v35, v33
	s_waitcnt lgkmcnt(0)
	v_max_f32_e32 v34, v34, v34
	v_max_f32_e32 v32, v32, v34
	ds_bpermute_b32 v34, v141, v32
	s_waitcnt lgkmcnt(0)
	v_max3_f32 v134, v145, v32, v34
	v_sub_f32_e32 v32, v145, v134
	v_exp_f32_e32 v32, v32
	v_mov_b32_e32 v145, v134
	v_mul_f32_e32 v148, v148, v32
	v_pk_mul_f32 v[82:83], v[82:83], v[32:33] op_sel_hi:[1,0]
	v_pk_mul_f32 v[80:81], v[80:81], v[32:33] op_sel_hi:[1,0]
	v_pk_mul_f32 v[78:79], v[78:79], v[32:33] op_sel_hi:[1,0]
	v_pk_mul_f32 v[76:77], v[76:77], v[32:33] op_sel_hi:[1,0]
	v_pk_mul_f32 v[74:75], v[74:75], v[32:33] op_sel_hi:[1,0]
	v_pk_mul_f32 v[72:73], v[72:73], v[32:33] op_sel_hi:[1,0]
	v_pk_mul_f32 v[70:71], v[70:71], v[32:33] op_sel_hi:[1,0]
	v_pk_mul_f32 v[68:69], v[68:69], v[32:33] op_sel_hi:[1,0]
	v_sub_f32_e32 v32, v92, v134
	v_exp_f32_e32 v159, v32
	v_sub_f32_e32 v32, v104, v134
	v_exp_f32_e32 v156, v32
	v_sub_f32_e32 v32, v93, v134
	v_exp_f32_e32 v132, v32
	v_sub_f32_e32 v32, v105, v134
	v_exp_f32_e32 v34, v32
	v_sub_f32_e32 v32, v94, v134
	v_add_f32_e32 v133, v159, v156
	v_exp_f32_e32 v160, v32
	v_sub_f32_e32 v32, v106, v134
	v_add_f32_e32 v92, v132, v34
	v_add_f32_e32 v93, v133, v35
	v_exp_f32_e32 v35, v32
	v_sub_f32_e32 v32, v95, v134
	v_add_f32_e32 v118, v92, v92
	v_add_f32_e32 v119, v92, v93
	v_exp_f32_e32 v120, v32
	v_sub_f32_e32 v32, v107, v134
	v_exp_f32_e32 v118, v32
	v_add_f32_e32 v121, v160, v35
	v_mov_b32_e32 v32, v132
	v_add_f32_e32 v92, v120, v118
	v_add_f32_e32 v93, v121, v119
	s_nop 0
	v_add_f32_e32 v119, v92, v93

; DEVI float fexp2(float x) { return __builtin_amdgcn_exp2f(x); }
; template <int M> DEVI float shx(float v) { return __int_as_float(__builtin_amdgcn_ds_swizzle(__float_as_int(v), (M << 10) | 0x1f)); }
; DEVI float shx32(float v, int lane) { return __int_as_float(__builtin_amdgcn_ds_bpermute((lane ^ 32) << 2, __float_as_int(v))); }
; DEVI bf16x8 pack_p(const f32x4& a, const f32x4& b) { return as_bf8((u32x4){pk2(a[0], a[1]), pk2(a[2], a[3]), pk2(b[0], b[1]), pk2(b[2], b[3])}); }
; template <int NC, int KS, class MaskF>
; DEVI void attn_tile(const unsigned char* Kl, int krow, const unsigned char* Vl, const bf16x8 (&q)[NC][KS], f32x4 (&o)[NC][4],
;                     float (&mr)[NC], float (&lr)[NC], int idx, int quad, int mask_mode, bool lane_ok, const MaskF& mf) {
;     ...
;       float ps = 0.f;
;       f32x4 p0, p1;
; #pragma unroll
;       for (int j = 0; j < 4; ++j) { p0[j] = fexp2(s[c][0][j] - mr[c]); p1[j] = fexp2(s[c][1][j] - mr[c]); ps += p0[j] + p1[j]; }
;       if (__builtin_amdgcn_ballot_w64(!(ps <= 2048.f)) != 0ull) {
;         float mx = fmaxf(fmaxf(fmaxf(s[c][0][0], s[c][0][1]), fmaxf(s[c][0][2], s[c][0][3])), fmaxf(fmaxf(s[c][1][0], s[c][1][1]), fmaxf(s[c][1][2], s[c][1][3])));
;         mx = fmaxf(mx, shx<16>(mx)); mx = fmaxf(mx, shx32(mx, quad * 16 + idx));
;         const float mnew = fmaxf(mr[c], mx);
;         const float alpha = fexp2(mr[c] - mnew);
;         lr[c] *= alpha; mr[c] = mnew;
; #pragma unroll
;         for (int dvt = 0; dvt < 4; ++dvt) o[c][dvt] *= alpha;
;         ps = 0.f;
; #pragma unroll
;         for (int j = 0; j < 4; ++j) { p0[j] = fexp2(s[c][0][j] - mnew); p1[j] = fexp2(s[c][1][j] - mnew); ps += p0[j] + p1[j]; }
;       }
;       lr[c] += ps;
;       s[c][0] = p0; s[c][1] = p1;
;       pb[c] = pack_p(s[c][0], s[c][1]);
.LBB0_1452:
	s_or_b64 exec, exec, s[4:5]
	v_sub_f32_e32 v32, v96, v146
	v_exp_f32_e32 v120, v32
	v_sub_f32_e32 v32, v100, v146
	v_exp_f32_e32 v118, v32
	v_sub_f32_e32 v32, v97, v146
	v_sub_f32_e32 v34, v101, v146
	v_exp_f32_e32 v32, v32
	v_exp_f32_e32 v34, v34
	v_add_f32_e32 v35, v118, v120
	v_add_f32_e32 v104, v34, v32
	v_add_f32_e32 v105, v35, v33
	v_sub_f32_e32 v35, v98, v146
	v_add_f32_e32 v106, v104, v104
	v_add_f32_e32 v107, v104, v105
	v_exp_f32_e32 v121, v35
	v_sub_f32_e32 v35, v102, v146
	v_sub_f32_e32 v104, v99, v146
	v_exp_f32_e32 v35, v35
	v_exp_f32_e32 v106, v104
	v_sub_f32_e32 v104, v103, v146
	v_exp_f32_e32 v104, v104
	v_add_f32_e32 v105, v35, v121
	v_add_f32_e32 v132, v104, v106
	v_add_f32_e32 v133, v105, v107
	s_nop 0
	v_add_f32_e32 v156, v132, v133
	v_cmp_nge_f32_e32 vcc, s94, v156
	s_cbranch_vccz .LBB0_1454
	v_max_f32_e32 v32, v97, v97
	v_max_f32_e32 v34, v96, v96
	v_max_f32_e32 v32, v34, v32
	v_max_f32_e32 v34, v99, v99
	v_max_f32_e32 v35, v98, v98
	v_max_f32_e32 v34, v35, v34
	v_max_f32_e32 v35, v103, v103
	v_max_f32_e32 v104, v102, v102
	v_max_f32_e32 v35, v104, v35
	v_max3_f32 v35, v100, v101, v35
	v_max3_f32 v32, v32, v34, v35
	ds_swizzle_b32 v34, v32 offset:swizzle(SWAP,16)
	v_mov_b32_e32 v35, v33
	s_waitcnt lgkmcnt(0)
	v_max_f32_e32 v34, v34, v34
	v_max_f32_e32 v32, v32, v34
	ds_bpermute_b32 v34, v141, v32
	s_waitcnt lgkmcnt(0)
	v_max3_f32 v134, v146, v32, v34
	v_sub_f32_e32 v32, v146, v134
	v_exp_f32_e32 v32, v32
	v_mov_b32_e32 v146, v134
	v_mul_f32_e32 v117, v117, v32
	v_pk_mul_f32 v[66:67], v[66:67], v[32:33] op_sel_hi:[1,0]
	v_pk_mul_f32 v[64:65], v[64:65], v[32:33] op_sel_hi:[1,0]
	v_pk_mul_f32 v[62:63], v[62:63], v[32:33] op_sel_hi:[1,0]
	v_pk_mul_f32 v[60:61], v[60:61], v[32:33] op_sel_hi:[1,0]
	v_pk_mul_f32 v[58:59], v[58:59], v[32:33] op_sel_hi:[1,0]
	v_pk_mul_f32 v[56:57], v[56:57], v[32:33] op_sel_hi:[1,0]
	v_pk_mul_f32 v[54:55], v[54:55], v[32:33] op_sel_hi:[1,0]
	v_pk_mul_f32 v[52:53], v[52:53], v[32:33] op_sel_hi:[1,0]
	v_sub_f32_e32 v32, v96, v134
	v_exp_f32_e32 v120, v32
	v_sub_f32_e32 v32, v100, v134
	v_exp_f32_e32 v118, v32
	v_sub_f32_e32 v32, v97, v134
	v_exp_f32_e32 v132, v32
	v_sub_f32_e32 v32, v101, v134
	v_exp_f32_e32 v34, v32
	v_sub_f32_e32 v32, v98, v134
	v_add_f32_e32 v133, v120, v118
	v_exp_f32_e32 v121, v32
	v_sub_f32_e32 v32, v102, v134
	v_add_f32_e32 v96, v132, v34
	v_add_f32_e32 v97, v133, v35
	v_exp_f32_e32 v35, v32
	v_sub_f32_e32 v32, v99, v134
	v_add_f32_e32 v104, v96, v96
	v_add_f32_e32 v105, v96, v97
	v_exp_f32_e32 v106, v32
	v_sub_f32_e32 v32, v103, v134
	v_exp_f32_e32 v104, v32
	v_add_f32_e32 v107, v121, v35
	v_mov_b32_e32 v32, v132
	v_add_f32_e32 v96, v106, v104
	v_add_f32_e32 v97, v107, v105
	s_nop 0
	v_add_f32_e32 v156, v96, v97

; DEVI float fexp2(float x) { return __builtin_amdgcn_exp2f(x); }
; template <int M> DEVI float shx(float v) { return __int_as_float(__builtin_amdgcn_ds_swizzle(__float_as_int(v), (M << 10) | 0x1f)); }
; DEVI float shx32(float v, int lane) { return __int_as_float(__builtin_amdgcn_ds_bpermute((lane ^ 32) << 2, __float_as_int(v))); }
; DEVI bf16x8 pack_p(const f32x4& a, const f32x4& b) { return as_bf8((u32x4){pk2(a[0], a[1]), pk2(a[2], a[3]), pk2(b[0], b[1]), pk2(b[2], b[3])}); }
; template <int NC, int KS, class MaskF>
; DEVI void attn_tile(const unsigned char* Kl, int krow, const unsigned char* Vl, const bf16x8 (&q)[NC][KS], f32x4 (&o)[NC][4],
;                     float (&mr)[NC], float (&lr)[NC], int idx, int quad, int mask_mode, bool lane_ok, const MaskF& mf) {
;     ...
;       float ps = 0.f;
;       f32x4 p0, p1;
; #pragma unroll
;       for (int j = 0; j < 4; ++j) { p0[j] = fexp2(s[c][0][j] - mr[c]); p1[j] = fexp2(s[c][1][j] - mr[c]); ps += p0[j] + p1[j]; }
;       if (__builtin_amdgcn_ballot_w64(!(ps <= 2048.f)) != 0ull) {
;         float mx = fmaxf(fmaxf(fmaxf(s[c][0][0], s[c][0][1]), fmaxf(s[c][0][2], s[c][0][3])), fmaxf(fmaxf(s[c][1][0], s[c][1][1]), fmaxf(s[c][1][2], s[c][1][3])));
;         mx = fmaxf(mx, shx<16>(mx)); mx = fmaxf(mx, shx32(mx, quad * 16 + idx));
;         const float mnew = fmaxf(mr[c], mx);
;         const float alpha = fexp2(mr[c] - mnew);
;         lr[c] *= alpha; mr[c] = mnew;
; #pragma unroll
;         for (int dvt = 0; dvt < 4; ++dvt) o[c][dvt] *= alpha;
;         ps = 0.f;
; #pragma unroll
;         for (int j = 0; j < 4; ++j) { p0[j] = fexp2(s[c][0][j] - mnew); p1[j] = fexp2(s[c][1][j] - mnew); ps += p0[j] + p1[j]; }
;       }
;       lr[c] += ps;
;       s[c][0] = p0; s[c][1] = p1;
;       pb[c] = pack_p(s[c][0], s[c][1]);
.LBB0_1460:
	s_or_b64 exec, exec, s[4:5]
	v_sub_f32_e32 v32, v84, v147
	v_exp_f32_e32 v104, v32
	v_sub_f32_e32 v32, v88, v147
	v_exp_f32_e32 v105, v32
	v_sub_f32_e32 v32, v85, v147
	v_sub_f32_e32 v34, v89, v147
	v_exp_f32_e32 v32, v32
	v_exp_f32_e32 v34, v34
	v_add_f32_e32 v35, v105, v104
	v_sub_f32_e32 v102, v91, v147
	v_exp_f32_e32 v102, v102
	v_add_f32_e32 v100, v34, v32
	v_add_f32_e32 v101, v35, v33
	v_sub_f32_e32 v35, v86, v147
	v_add_f32_e32 v101, v100, v101
	v_add_f32_e32 v100, v100, v100
	v_sub_f32_e32 v100, v90, v147
	v_exp_f32_e32 v35, v35
	v_exp_f32_e32 v106, v100
	v_sub_f32_e32 v100, v87, v147
	v_exp_f32_e32 v100, v100
	v_add_f32_e32 v103, v106, v35
	v_add_f32_e32 v120, v102, v100
	v_add_f32_e32 v121, v103, v101
	s_nop 0
	v_add_f32_e32 v155, v120, v121
	v_cmp_nge_f32_e32 vcc, s94, v155
	s_cbranch_vccz .LBB0_1462
	v_max_f32_e32 v32, v85, v85
	v_max_f32_e32 v34, v84, v84
	v_max_f32_e32 v32, v34, v32
	v_max_f32_e32 v34, v87, v87
	v_max_f32_e32 v35, v86, v86
	v_max_f32_e32 v34, v35, v34
	v_max_f32_e32 v35, v91, v91
	v_max_f32_e32 v100, v90, v90
	v_max_f32_e32 v35, v100, v35
	v_max3_f32 v35, v88, v89, v35
	v_max3_f32 v32, v32, v34, v35
	ds_swizzle_b32 v34, v32 offset:swizzle(SWAP,16)
	v_mov_b32_e32 v35, v33
	s_waitcnt lgkmcnt(0)
	v_max_f32_e32 v34, v34, v34
	v_max_f32_e32 v32, v32, v34
	ds_bpermute_b32 v34, v141, v32
	s_waitcnt lgkmcnt(0)
	v_max3_f32 v107, v147, v32, v34
	v_sub_f32_e32 v32, v147, v107
	v_exp_f32_e32 v32, v32
	v_mov_b32_e32 v147, v107
	v_mul_f32_e32 v116, v116, v32
	v_pk_mul_f32 v[50:51], v[50:51], v[32:33] op_sel_hi:[1,0]
	v_pk_mul_f32 v[48:49], v[48:49], v[32:33] op_sel_hi:[1,0]
	v_pk_mul_f32 v[46:47], v[46:47], v[32:33] op_sel_hi:[1,0]
	v_pk_mul_f32 v[44:45], v[44:45], v[32:33] op_sel_hi:[1,0]
	v_pk_mul_f32 v[42:43], v[42:43], v[32:33] op_sel_hi:[1,0]
	v_pk_mul_f32 v[40:41], v[40:41], v[32:33] op_sel_hi:[1,0]
	v_pk_mul_f32 v[38:39], v[38:39], v[32:33] op_sel_hi:[1,0]
	v_pk_mul_f32 v[36:37], v[36:37], v[32:33] op_sel_hi:[1,0]
	v_sub_f32_e32 v32, v84, v107
	v_exp_f32_e32 v104, v32
	v_sub_f32_e32 v32, v88, v107
	v_exp_f32_e32 v105, v32
	v_sub_f32_e32 v32, v85, v107
	v_exp_f32_e32 v120, v32
	v_sub_f32_e32 v32, v89, v107
	v_exp_f32_e32 v34, v32
	v_add_f32_e32 v121, v104, v105
	v_sub_f32_e32 v32, v86, v107
	v_add_f32_e32 v84, v120, v34
	v_add_f32_e32 v85, v121, v35
	v_exp_f32_e32 v35, v32
	v_sub_f32_e32 v32, v90, v107
	v_exp_f32_e32 v106, v32
	v_sub_f32_e32 v32, v87, v107
	v_add_f32_e32 v102, v84, v84
	v_add_f32_e32 v103, v84, v85
	v_exp_f32_e32 v100, v32
	v_sub_f32_e32 v32, v91, v107
	v_exp_f32_e32 v102, v32
	v_add_f32_e32 v101, v35, v106
	v_mov_b32_e32 v32, v120
	v_add_f32_e32 v84, v100, v102
	v_add_f32_e32 v85, v101, v103
	s_nop 0
	v_add_f32_e32 v155, v84, v85

; DEVI float fexp2(float x) { return __builtin_amdgcn_exp2f(x); }
; template <int M> DEVI float shx(float v) { return __int_as_float(__builtin_amdgcn_ds_swizzle(__float_as_int(v), (M << 10) | 0x1f)); }
; DEVI float shx32(float v, int lane) { return __int_as_float(__builtin_amdgcn_ds_bpermute((lane ^ 32) << 2, __float_as_int(v))); }
; DEVI bf16x8 pack_p(const f32x4& a, const f32x4& b) { return as_bf8((u32x4){pk2(a[0], a[1]), pk2(a[2], a[3]), pk2(b[0], b[1]), pk2(b[2], b[3])}); }
; template <int NC, int KS, class MaskF>
; DEVI void attn_tile(const unsigned char* Kl, int krow, const unsigned char* Vl, const bf16x8 (&q)[NC][KS], f32x4 (&o)[NC][4],
;                     float (&mr)[NC], float (&lr)[NC], int idx, int quad, int mask_mode, bool lane_ok, const MaskF& mf) {
;     ...
;       float ps = 0.f;
;       f32x4 p0, p1;
; #pragma unroll
;       for (int j = 0; j < 4; ++j) { p0[j] = fexp2(s[c][0][j] - mr[c]); p1[j] = fexp2(s[c][1][j] - mr[c]); ps += p0[j] + p1[j]; }
;       if (__builtin_amdgcn_ballot_w64(!(ps <= 2048.f)) != 0ull) {
;         float mx = fmaxf(fmaxf(fmaxf(s[c][0][0], s[c][0][1]), fmaxf(s[c][0][2], s[c][0][3])), fmaxf(fmaxf(s[c][1][0], s[c][1][1]), fmaxf(s[c][1][2], s[c][1][3])));
;         mx = fmaxf(mx, shx<16>(mx)); mx = fmaxf(mx, shx32(mx, quad * 16 + idx));
;         const float mnew = fmaxf(mr[c], mx);
;         const float alpha = fexp2(mr[c] - mnew);
;         lr[c] *= alpha; mr[c] = mnew;
; #pragma unroll
;         for (int dvt = 0; dvt < 4; ++dvt) o[c][dvt] *= alpha;
;         ps = 0.f;
; #pragma unroll
;         for (int j = 0; j < 4; ++j) { p0[j] = fexp2(s[c][0][j] - mnew); p1[j] = fexp2(s[c][1][j] - mnew); ps += p0[j] + p1[j]; }
;       }
;       lr[c] += ps;
;       s[c][0] = p0; s[c][1] = p1;
;       pb[c] = pack_p(s[c][0], s[c][1]);
.LBB0_1468:
	s_or_b64 exec, exec, s[4:5]
	v_sub_f32_e32 v32, v92, v145
	v_exp_f32_e32 v164, v32
	v_sub_f32_e32 v32, v104, v145
	v_exp_f32_e32 v163, v32
	v_sub_f32_e32 v32, v93, v145
	v_sub_f32_e32 v38, v105, v145
	v_exp_f32_e32 v32, v32
	v_exp_f32_e32 v38, v38
	v_add_f32_e32 v39, v163, v164
	v_sub_f32_e32 v118, v95, v145
	v_add_f32_e32 v148, v148, v119
	v_add_f32_e32 v120, v38, v32
	v_add_f32_e32 v121, v39, v33
	v_sub_f32_e32 v39, v94, v145
	v_add_f32_e32 v121, v120, v121
	v_add_f32_e32 v120, v120, v120
	v_exp_f32_e32 v165, v39
	v_sub_f32_e32 v39, v106, v145
	v_exp_f32_e32 v39, v39
	v_exp_f32_e32 v120, v118
	v_sub_f32_e32 v118, v107, v145
	v_exp_f32_e32 v118, v118
	v_add_f32_e32 v119, v39, v165
	v_add_f32_e32 v132, v118, v120
	v_add_f32_e32 v133, v119, v121
	s_nop 0
	v_add_f32_e32 v119, v132, v133
	v_cmp_nge_f32_e32 vcc, s94, v119
	s_cbranch_vccz .LBB0_1470
	v_max_f32_e32 v32, v93, v93
	v_max_f32_e32 v38, v92, v92
	v_max_f32_e32 v32, v38, v32
	v_max_f32_e32 v38, v95, v95
	v_max_f32_e32 v39, v94, v94
	v_max_f32_e32 v38, v39, v38
	v_max_f32_e32 v39, v107, v107
	v_max_f32_e32 v118, v106, v106
	v_max_f32_e32 v39, v118, v39
	v_max3_f32 v39, v104, v105, v39
	v_max3_f32 v32, v32, v38, v39
	ds_swizzle_b32 v38, v32 offset:swizzle(SWAP,16)
	v_mov_b32_e32 v39, v33
	s_waitcnt lgkmcnt(0)
	v_max_f32_e32 v38, v38, v38
	v_max_f32_e32 v32, v32, v38
	ds_bpermute_b32 v38, v141, v32
	s_waitcnt lgkmcnt(0)
	v_max3_f32 v134, v145, v32, v38
	v_sub_f32_e32 v32, v145, v134
	v_exp_f32_e32 v32, v32
	v_mov_b32_e32 v145, v134
	v_mul_f32_e32 v148, v148, v32
	v_pk_mul_f32 v[82:83], v[82:83], v[32:33] op_sel_hi:[1,0]
	v_pk_mul_f32 v[80:81], v[80:81], v[32:33] op_sel_hi:[1,0]
	v_pk_mul_f32 v[78:79], v[78:79], v[32:33] op_sel_hi:[1,0]
	v_pk_mul_f32 v[76:77], v[76:77], v[32:33] op_sel_hi:[1,0]
	v_pk_mul_f32 v[74:75], v[74:75], v[32:33] op_sel_hi:[1,0]
	v_pk_mul_f32 v[72:73], v[72:73], v[32:33] op_sel_hi:[1,0]
	v_pk_mul_f32 v[70:71], v[70:71], v[32:33] op_sel_hi:[1,0]
	v_pk_mul_f32 v[68:69], v[68:69], v[32:33] op_sel_hi:[1,0]
	v_sub_f32_e32 v32, v92, v134
	v_exp_f32_e32 v164, v32
	v_sub_f32_e32 v32, v104, v134
	v_exp_f32_e32 v163, v32
	v_sub_f32_e32 v32, v93, v134
	v_exp_f32_e32 v132, v32
	v_sub_f32_e32 v32, v105, v134
	v_exp_f32_e32 v38, v32
	v_sub_f32_e32 v32, v94, v134
	v_add_f32_e32 v133, v164, v163
	v_exp_f32_e32 v165, v32
	v_sub_f32_e32 v32, v106, v134
	v_add_f32_e32 v92, v132, v38
	v_add_f32_e32 v93, v133, v39
	v_exp_f32_e32 v39, v32
	v_sub_f32_e32 v32, v95, v134
	v_add_f32_e32 v118, v92, v92
	v_add_f32_e32 v119, v92, v93
	v_exp_f32_e32 v120, v32
	v_sub_f32_e32 v32, v107, v134
	v_exp_f32_e32 v118, v32
	v_add_f32_e32 v121, v165, v39
	v_mov_b32_e32 v32, v132
	v_add_f32_e32 v92, v120, v118
	v_add_f32_e32 v93, v121, v119
	s_nop 0
	v_add_f32_e32 v119, v92, v93

; DEVI float fexp2(float x) { return __builtin_amdgcn_exp2f(x); }
; template <int M> DEVI float shx(float v) { return __int_as_float(__builtin_amdgcn_ds_swizzle(__float_as_int(v), (M << 10) | 0x1f)); }
; DEVI float shx32(float v, int lane) { return __int_as_float(__builtin_amdgcn_ds_bpermute((lane ^ 32) << 2, __float_as_int(v))); }
; DEVI bf16x8 pack_p(const f32x4& a, const f32x4& b) { return as_bf8((u32x4){pk2(a[0], a[1]), pk2(a[2], a[3]), pk2(b[0], b[1]), pk2(b[2], b[3])}); }
; template <int NC, int KS, class MaskF>
; DEVI void attn_tile(const unsigned char* Kl, int krow, const unsigned char* Vl, const bf16x8 (&q)[NC][KS], f32x4 (&o)[NC][4],
;                     float (&mr)[NC], float (&lr)[NC], int idx, int quad, int mask_mode, bool lane_ok, const MaskF& mf) {
;     ...
;       float ps = 0.f;
;       f32x4 p0, p1;
; #pragma unroll
;       for (int j = 0; j < 4; ++j) { p0[j] = fexp2(s[c][0][j] - mr[c]); p1[j] = fexp2(s[c][1][j] - mr[c]); ps += p0[j] + p1[j]; }
;       if (__builtin_amdgcn_ballot_w64(!(ps <= 2048.f)) != 0ull) {
;         float mx = fmaxf(fmaxf(fmaxf(s[c][0][0], s[c][0][1]), fmaxf(s[c][0][2], s[c][0][3])), fmaxf(fmaxf(s[c][1][0], s[c][1][1]), fmaxf(s[c][1][2], s[c][1][3])));
;         mx = fmaxf(mx, shx<16>(mx)); mx = fmaxf(mx, shx32(mx, quad * 16 + idx));
;         const float mnew = fmaxf(mr[c], mx);
;         const float alpha = fexp2(mr[c] - mnew);
;         lr[c] *= alpha; mr[c] = mnew;
; #pragma unroll
;         for (int dvt = 0; dvt < 4; ++dvt) o[c][dvt] *= alpha;
;         ps = 0.f;
; #pragma unroll
;         for (int j = 0; j < 4; ++j) { p0[j] = fexp2(s[c][0][j] - mnew); p1[j] = fexp2(s[c][1][j] - mnew); ps += p0[j] + p1[j]; }
;       }
;       lr[c] += ps;
;       s[c][0] = p0; s[c][1] = p1;
;       pb[c] = pack_p(s[c][0], s[c][1]);
.LBB0_1476:
	s_or_b64 exec, exec, s[4:5]
	v_sub_f32_e32 v32, v96, v146
	v_exp_f32_e32 v120, v32
	v_sub_f32_e32 v32, v100, v146
	v_exp_f32_e32 v118, v32
	v_sub_f32_e32 v32, v97, v146
	v_sub_f32_e32 v38, v101, v146
	v_exp_f32_e32 v32, v32
	v_exp_f32_e32 v38, v38
	v_add_f32_e32 v39, v118, v120
	v_add_f32_e32 v117, v117, v156
	v_add_f32_e32 v104, v38, v32
	v_add_f32_e32 v105, v39, v33
	v_sub_f32_e32 v39, v98, v146
	v_add_f32_e32 v106, v104, v104
	v_add_f32_e32 v107, v104, v105
	v_exp_f32_e32 v121, v39
	v_sub_f32_e32 v39, v102, v146
	v_sub_f32_e32 v104, v99, v146
	v_exp_f32_e32 v39, v39
	v_exp_f32_e32 v106, v104
	v_sub_f32_e32 v104, v103, v146
	v_exp_f32_e32 v104, v104
	v_add_f32_e32 v105, v39, v121
	v_add_f32_e32 v132, v104, v106
	v_add_f32_e32 v133, v105, v107
	s_nop 0
	v_add_f32_e32 v105, v132, v133
	v_cmp_nge_f32_e32 vcc, s94, v105
	s_cbranch_vccz .LBB0_1478
	v_max_f32_e32 v32, v97, v97
	v_max_f32_e32 v38, v96, v96
	v_max_f32_e32 v32, v38, v32
	v_max_f32_e32 v38, v99, v99
	v_max_f32_e32 v39, v98, v98
	v_max_f32_e32 v38, v39, v38
	v_max_f32_e32 v39, v103, v103
	v_max_f32_e32 v104, v102, v102
	v_max_f32_e32 v39, v104, v39
	v_max3_f32 v39, v100, v101, v39
	v_max3_f32 v32, v32, v38, v39
	ds_swizzle_b32 v38, v32 offset:swizzle(SWAP,16)
	v_mov_b32_e32 v39, v33
	s_waitcnt lgkmcnt(0)
	v_max_f32_e32 v38, v38, v38
	v_max_f32_e32 v32, v32, v38
	ds_bpermute_b32 v38, v141, v32
	s_waitcnt lgkmcnt(0)
	v_max3_f32 v134, v146, v32, v38
	v_sub_f32_e32 v32, v146, v134
	v_exp_f32_e32 v32, v32
	v_mov_b32_e32 v146, v134
	v_mul_f32_e32 v117, v117, v32
	v_pk_mul_f32 v[66:67], v[66:67], v[32:33] op_sel_hi:[1,0]
	v_pk_mul_f32 v[64:65], v[64:65], v[32:33] op_sel_hi:[1,0]
	v_pk_mul_f32 v[62:63], v[62:63], v[32:33] op_sel_hi:[1,0]
	v_pk_mul_f32 v[60:61], v[60:61], v[32:33] op_sel_hi:[1,0]
	v_pk_mul_f32 v[58:59], v[58:59], v[32:33] op_sel_hi:[1,0]
	v_pk_mul_f32 v[56:57], v[56:57], v[32:33] op_sel_hi:[1,0]
	v_pk_mul_f32 v[54:55], v[54:55], v[32:33] op_sel_hi:[1,0]
	v_pk_mul_f32 v[52:53], v[52:53], v[32:33] op_sel_hi:[1,0]
	v_sub_f32_e32 v32, v96, v134
	v_exp_f32_e32 v120, v32
	v_sub_f32_e32 v32, v100, v134
	v_exp_f32_e32 v118, v32
	v_sub_f32_e32 v32, v97, v134
	v_exp_f32_e32 v132, v32
	v_sub_f32_e32 v32, v101, v134
	v_exp_f32_e32 v38, v32
	v_sub_f32_e32 v32, v98, v134
	v_add_f32_e32 v133, v120, v118
	v_exp_f32_e32 v121, v32
	v_sub_f32_e32 v32, v102, v134
	v_add_f32_e32 v96, v132, v38
	v_add_f32_e32 v97, v133, v39
	v_exp_f32_e32 v39, v32
	v_sub_f32_e32 v32, v99, v134
	v_add_f32_e32 v104, v96, v96
	v_add_f32_e32 v105, v96, v97
	v_exp_f32_e32 v106, v32
	v_sub_f32_e32 v32, v103, v134
	v_exp_f32_e32 v104, v32
	v_add_f32_e32 v107, v121, v39
	v_mov_b32_e32 v32, v132
	v_add_f32_e32 v96, v106, v104
	v_add_f32_e32 v97, v107, v105
	s_nop 0
	v_add_f32_e32 v105, v96, v97

; DEVI float fexp2(float x) { return __builtin_amdgcn_exp2f(x); }
; template <int M> DEVI float shx(float v) { return __int_as_float(__builtin_amdgcn_ds_swizzle(__float_as_int(v), (M << 10) | 0x1f)); }
; DEVI float shx32(float v, int lane) { return __int_as_float(__builtin_amdgcn_ds_bpermute((lane ^ 32) << 2, __float_as_int(v))); }
; DEVI bf16x8 pack_p(const f32x4& a, const f32x4& b) { return as_bf8((u32x4){pk2(a[0], a[1]), pk2(a[2], a[3]), pk2(b[0], b[1]), pk2(b[2], b[3])}); }
; template <int NC, int KS, class MaskF>
; DEVI void attn_tile(const unsigned char* Kl, int krow, const unsigned char* Vl, const bf16x8 (&q)[NC][KS], f32x4 (&o)[NC][4],
;                     float (&mr)[NC], float (&lr)[NC], int idx, int quad, int mask_mode, bool lane_ok, const MaskF& mf) {
;     ...
;       float ps = 0.f;
;       f32x4 p0, p1;
; #pragma unroll
;       for (int j = 0; j < 4; ++j) { p0[j] = fexp2(s[c][0][j] - mr[c]); p1[j] = fexp2(s[c][1][j] - mr[c]); ps += p0[j] + p1[j]; }
;       if (__builtin_amdgcn_ballot_w64(!(ps <= 2048.f)) != 0ull) {
;         float mx = fmaxf(fmaxf(fmaxf(s[c][0][0], s[c][0][1]), fmaxf(s[c][0][2], s[c][0][3])), fmaxf(fmaxf(s[c][1][0], s[c][1][1]), fmaxf(s[c][1][2], s[c][1][3])));
;         mx = fmaxf(mx, shx<16>(mx)); mx = fmaxf(mx, shx32(mx, quad * 16 + idx));
;         const float mnew = fmaxf(mr[c], mx);
;         const float alpha = fexp2(mr[c] - mnew);
;         lr[c] *= alpha; mr[c] = mnew;
; #pragma unroll
;         for (int dvt = 0; dvt < 4; ++dvt) o[c][dvt] *= alpha;
;         ps = 0.f;
; #pragma unroll
;         for (int j = 0; j < 4; ++j) { p0[j] = fexp2(s[c][0][j] - mnew); p1[j] = fexp2(s[c][1][j] - mnew); ps += p0[j] + p1[j]; }
;       }
;       lr[c] += ps;
;       s[c][0] = p0; s[c][1] = p1;
;       pb[c] = pack_p(s[c][0], s[c][1]);
.LBB0_1484:
	s_or_b64 exec, exec, s[4:5]
	v_sub_f32_e32 v32, v84, v147
	v_exp_f32_e32 v106, v32
	v_sub_f32_e32 v32, v88, v147
	v_exp_f32_e32 v107, v32
	v_sub_f32_e32 v32, v85, v147
	v_sub_f32_e32 v38, v89, v147
	v_exp_f32_e32 v32, v32
	v_exp_f32_e32 v38, v38
	v_add_f32_e32 v39, v107, v106
	v_sub_f32_e32 v102, v91, v147
	v_exp_f32_e32 v102, v102
	v_add_f32_e32 v100, v38, v32
	v_add_f32_e32 v101, v39, v33
	v_sub_f32_e32 v39, v86, v147
	v_add_f32_e32 v101, v100, v101
	v_add_f32_e32 v100, v100, v100
	v_sub_f32_e32 v100, v90, v147
	v_exp_f32_e32 v39, v39
	v_exp_f32_e32 v113, v100
	v_sub_f32_e32 v100, v87, v147
	v_exp_f32_e32 v100, v100
	v_add_f32_e32 v104, v116, v155
	v_add_f32_e32 v103, v113, v39
	v_add_f32_e32 v120, v102, v100
	v_add_f32_e32 v121, v103, v101
	s_nop 0
	v_add_f32_e32 v101, v120, v121
	v_cmp_nge_f32_e32 vcc, s94, v101
	s_cbranch_vccz .LBB0_1486
	v_max_f32_e32 v32, v85, v85
	v_max_f32_e32 v38, v84, v84
	v_max_f32_e32 v32, v38, v32
	v_max_f32_e32 v38, v87, v87
	v_max_f32_e32 v39, v86, v86
	v_max_f32_e32 v38, v39, v38
	v_max_f32_e32 v39, v91, v91
	v_max_f32_e32 v100, v90, v90
	v_max_f32_e32 v39, v100, v39
	v_max3_f32 v39, v88, v89, v39
	v_max3_f32 v32, v32, v38, v39
	ds_swizzle_b32 v38, v32 offset:swizzle(SWAP,16)
	v_mov_b32_e32 v39, v33
	s_waitcnt lgkmcnt(0)
	v_max_f32_e32 v38, v38, v38
	v_max_f32_e32 v32, v32, v38
	ds_bpermute_b32 v38, v141, v32
	s_waitcnt lgkmcnt(0)
	v_max3_f32 v116, v147, v32, v38
	v_sub_f32_e32 v32, v147, v116
	v_exp_f32_e32 v32, v32
	v_mov_b32_e32 v147, v116
	v_mul_f32_e32 v104, v104, v32
	v_pk_mul_f32 v[50:51], v[50:51], v[32:33] op_sel_hi:[1,0]
	v_pk_mul_f32 v[48:49], v[48:49], v[32:33] op_sel_hi:[1,0]
	v_pk_mul_f32 v[46:47], v[46:47], v[32:33] op_sel_hi:[1,0]
	v_pk_mul_f32 v[44:45], v[44:45], v[32:33] op_sel_hi:[1,0]
	v_pk_mul_f32 v[42:43], v[42:43], v[32:33] op_sel_hi:[1,0]
	v_pk_mul_f32 v[40:41], v[40:41], v[32:33] op_sel_hi:[1,0]
	v_pk_mul_f32 v[36:37], v[36:37], v[32:33] op_sel_hi:[1,0]
	v_pk_mul_f32 v[34:35], v[34:35], v[32:33] op_sel_hi:[1,0]
	v_sub_f32_e32 v32, v84, v116
	v_exp_f32_e32 v106, v32
	v_sub_f32_e32 v32, v88, v116
	v_exp_f32_e32 v107, v32
	v_sub_f32_e32 v32, v85, v116
	v_exp_f32_e32 v120, v32
	v_sub_f32_e32 v32, v89, v116
	v_exp_f32_e32 v38, v32
	v_add_f32_e32 v121, v106, v107
	v_sub_f32_e32 v32, v86, v116
	v_add_f32_e32 v84, v120, v38
	v_add_f32_e32 v85, v121, v39
	v_exp_f32_e32 v39, v32
	v_sub_f32_e32 v32, v90, v116
	v_exp_f32_e32 v113, v32
	v_sub_f32_e32 v32, v87, v116
	v_add_f32_e32 v102, v84, v84
	v_add_f32_e32 v103, v84, v85
	v_exp_f32_e32 v100, v32
	v_sub_f32_e32 v32, v91, v116
	v_exp_f32_e32 v102, v32
	v_add_f32_e32 v101, v39, v113
	v_mov_b32_e32 v32, v120
	v_add_f32_e32 v84, v100, v102
	v_add_f32_e32 v85, v101, v103
	s_nop 0
	v_add_f32_e32 v101, v84, v85
